# GCONV: skip the second-A-half MFMA bursts in the 43 tiles of the 33rd M-tile row (their rows 128..255 are the zero halo; exact)
# baseline (speedup 1.0000x reference)
; #define PG8_STAGE(bufoff, gbase, voff) do { _Pragma("unroll") for (int _i = 0; _i < 2; ++_i) \
;         __builtin_amdgcn_global_load_lds((const unsigned*)((const char*)(gbase) + (voff)[_i]), (PG8_LAS unsigned*)(lds + (bufoff) + ldsw + _i * 8192), 16, 0, 0); } while (0)
; #define PG8_LDA(dst, b, h) do { _Pragma("unroll") for (int m = 0; m < 4; ++m) _Pragma("unroll") for (int k = 0; k < 2; ++k) dst[m][k] = *(const PG8_LAS bf16x8*)(lds + PG8_SA(b, h) + aoff + m * 2048 + k * 1024); } while (0)
; #define PG8_LDB(dst, b, h) do { _Pragma("unroll") for (int n = 0; n < 2; ++n) _Pragma("unroll") for (int k = 0; k < 2; ++k) dst[n][k] = *(const PG8_LAS bf16x8*)(lds + PG8_SB(b, h) + boff + n * 2048 + k * 1024); } while (0)
; #define PG8_MMA(ai, bj, At, Bt) do { __builtin_amdgcn_s_setprio(1); _Pragma("unroll") for (int m = 0; m < 4; ++m) _Pragma("unroll") for (int n = 0; n < 2; ++n) _Pragma("unroll") for (int k = 0; k < 2; ++k) \
;         acc[ai][bj][m][n] = __builtin_amdgcn_mfma_f32_16x16x32_bf16(Bt[n][k], At[m][k], acc[ai][bj][m][n], 0, 0, 0); __builtin_amdgcn_s_setprio(0); } while (0)
; #define PG8_WAIT_V(n) asm volatile("s_waitcnt vmcnt(" #n ")" ::: "memory")
; #define PG8_WAIT_L(n) asm volatile("s_waitcnt lgkmcnt(" #n ")" ::: "memory")
; #define PG8_BAR __builtin_amdgcn_s_barrier()
; #define PG8_SCHED __builtin_amdgcn_sched_barrier(0)
; template <class Epi, class Sched, bool ALIGN_EPI = false, bool SP2 = false>
; __device__ __forceinline__ void gemm_phase(PG8_LAS unsigned char* lds, const Gemm g, const Sched& S, const Epi& E) {
;     ...
;             PG8_LDB(B0, 0, 0); PG8_LDB(B1, 0, 1); PG8_SCHED; PG8_LDA(At, 0, 0); PG8_STAGE(PG8_SA(1, 1), a1 + hstep, voffA);
;             PG8_WAIT_V(8); PG8_WAIT_L(0); PG8_BAR; PG8_MMA(0, 0, At, B0); PG8_MMA(0, 1, At, B1); PG8_BAR; PG8_SCHED;
;             PG8_LDA(At, 0, 1); PG8_STAGE(PG8_SB(0, 0), b2, voffB); PG8_STAGE(PG8_SB(0, 1), b2 + hstep, voffB); PG8_STAGE(PG8_SA(0, 0), a2, voffA);
;             PG8_WAIT_V(8); PG8_WAIT_L(0); PG8_BAR; PG8_MMA(1, 0, At, B0); PG8_MMA(1, 1, At, B1); PG8_BAR; PG8_SCHED;
.LBB0_365:
	s_add_i32 s88, s86, 2
	s_add_u32 s89, s0, 0x80
	s_addc_u32 s87, s1, 0
	s_cmp_eq_u32 s33, s86
	s_cselect_b32 s87, s3, s87
	s_cselect_b32 s86, s2, s89
	v_add_u32_e32 v0, s19, v230
	s_cselect_b32 vcc_hi, s85, s73
	s_cselect_b32 vcc_lo, s84, s72
	s_add_i32 s89, 0, 0x14000
	ds_read_b128 v[120:123], v0
	ds_read_b128 v[124:127], v0 offset:1024
	ds_read_b128 v[128:131], v0 offset:2048
	ds_read_b128 v[132:135], v0 offset:3072
	v_add_u32_e32 v0, s89, v230
	ds_read_b128 v[136:139], v0
	ds_read_b128 v[140:143], v0 offset:1024
	ds_read_b128 v[162:165], v0 offset:2048
	ds_read_b128 v[166:169], v0 offset:3072
	v_lshl_add_u64 v[144:145], s[0:1], 0, v[184:185]
	s_add_i32 m0, s93, 0xc000
	ds_read_b128 v[170:173], v238
	ds_read_b128 v[188:191], v238 offset:1024
	ds_read_b128 v[192:195], v238 offset:2048
	ds_read_b128 v[196:199], v238 offset:3072
	ds_read_b128 v[200:203], v238 offset:4096
	ds_read_b128 v[204:207], v238 offset:5120
	ds_read_b128 v[242:245], v238 offset:6144
	ds_read_b128 v[246:249], v238 offset:7168
	global_load_lds_dwordx4 v[144:145], off
	v_lshl_add_u64 v[144:145], s[0:1], 0, v[186:187]
	s_add_i32 m0, s93, 0xe000
	s_nop 0
	global_load_lds_dwordx4 v[144:145], off
	s_waitcnt vmcnt(8)
	s_waitcnt lgkmcnt(0)
	s_barrier
	s_setprio 1
	s_waitcnt lgkmcnt(0)
	v_mfma_f32_16x16x32_bf16 v[158:161], v[120:123], v[170:173], v[158:161]
	v_mfma_f32_16x16x32_bf16 v[158:161], v[124:127], v[188:191], v[158:161]
	v_mfma_f32_16x16x32_bf16 v[150:153], v[120:123], v[192:195], v[150:153]
	v_mfma_f32_16x16x32_bf16 v[150:153], v[124:127], v[196:199], v[150:153]
	v_mfma_f32_16x16x32_bf16 v[100:103], v[120:123], v[200:203], v[100:103]
	v_mfma_f32_16x16x32_bf16 v[100:103], v[124:127], v[204:207], v[100:103]
	v_mfma_f32_16x16x32_bf16 v[116:119], v[120:123], v[242:245], v[116:119]
	v_mfma_f32_16x16x32_bf16 v[116:119], v[124:127], v[246:249], v[116:119]
	v_mfma_f32_16x16x32_bf16 v[68:71], v[128:131], v[242:245], v[68:71]
	v_mfma_f32_16x16x32_bf16 v[68:71], v[132:135], v[246:249], v[68:71]
	v_mfma_f32_16x16x32_bf16 v[36:39], v[128:131], v[200:203], v[36:39]
	v_mfma_f32_16x16x32_bf16 v[36:39], v[132:135], v[204:207], v[36:39]
	v_mfma_f32_16x16x32_bf16 v[52:55], v[128:131], v[192:195], v[52:55]
	v_mfma_f32_16x16x32_bf16 v[52:55], v[132:135], v[196:199], v[52:55]
	v_mfma_f32_16x16x32_bf16 v[60:63], v[128:131], v[170:173], v[60:63]
	v_mfma_f32_16x16x32_bf16 v[60:63], v[132:135], v[188:191], v[60:63]
	s_setprio 0
	s_setprio 1
	v_mfma_f32_16x16x32_bf16 v[154:157], v[136:139], v[170:173], v[154:157]
	v_mfma_f32_16x16x32_bf16 v[154:157], v[140:143], v[188:191], v[154:157]
	v_mfma_f32_16x16x32_bf16 v[144:147], v[136:139], v[192:195], v[146:149]
	v_mfma_f32_16x16x32_bf16 v[144:147], v[140:143], v[196:199], v[144:147]
	v_mfma_f32_16x16x32_bf16 v[96:99], v[136:139], v[200:203], v[96:99]
	v_mfma_f32_16x16x32_bf16 v[96:99], v[140:143], v[204:207], v[96:99]
	v_mfma_f32_16x16x32_bf16 v[112:115], v[136:139], v[242:245], v[112:115]
	v_mfma_f32_16x16x32_bf16 v[112:115], v[140:143], v[246:249], v[112:115]
	v_mfma_f32_16x16x32_bf16 v[64:67], v[162:165], v[242:245], v[64:67]
	v_mfma_f32_16x16x32_bf16 v[64:67], v[166:169], v[246:249], v[64:67]
	v_mfma_f32_16x16x32_bf16 v[32:35], v[162:165], v[200:203], v[32:35]
	v_mfma_f32_16x16x32_bf16 v[32:35], v[166:169], v[204:207], v[32:35]
	v_mfma_f32_16x16x32_bf16 v[48:51], v[162:165], v[192:195], v[48:51]
	v_mfma_f32_16x16x32_bf16 v[48:51], v[166:169], v[196:199], v[48:51]
	v_mfma_f32_16x16x32_bf16 v[56:59], v[162:165], v[170:173], v[56:59]
	v_mfma_f32_16x16x32_bf16 v[56:59], v[166:169], v[188:191], v[56:59]
	s_setprio 0
	s_barrier
	s_add_i32 s38, s19, s92
	v_lshl_add_u64 v[174:175], vcc, 0, v[176:177]
	s_mov_b32 m0, s38
	ds_read_b128 v[170:173], v238 offset:16384
	ds_read_b128 v[188:191], v238 offset:17408
	ds_read_b128 v[192:195], v238 offset:18432
	ds_read_b128 v[196:199], v238 offset:19456
	ds_read_b128 v[200:203], v238 offset:20480
	ds_read_b128 v[204:207], v238 offset:21504
	ds_read_b128 v[242:245], v238 offset:22528
	ds_read_b128 v[246:249], v238 offset:23552
	global_load_lds_dwordx4 v[174:175], off
	s_add_i32 m0, s38, 0x2000
	v_lshl_add_u64 v[208:209], vcc, 0, v[180:181]
	s_add_u32 vcc_lo, vcc_lo, s48
	s_addc_u32 vcc_hi, vcc_hi, s49
	s_add_i32 s38, s89, s92
	global_load_lds_dwordx4 v[208:209], off
	v_lshl_add_u64 v[216:217], vcc, 0, v[176:177]
	s_mov_b32 m0, s38
	v_lshl_add_u64 v[224:225], vcc, 0, v[180:181]
	global_load_lds_dwordx4 v[216:217], off
	s_add_i32 m0, s38, 0x2000
	v_lshl_add_u64 v[226:227], s[86:87], 0, v[2:3]
	global_load_lds_dwordx4 v[224:225], off
	s_mov_b32 m0, s93
	v_lshl_add_u64 v[228:229], s[86:87], 0, v[178:179]
	global_load_lds_dwordx4 v[226:227], off
	s_mov_b32 m0, s94
	s_nop 0
	global_load_lds_dwordx4 v[228:229], off
	s_waitcnt vmcnt(8)
	s_waitcnt lgkmcnt(0)
	s_barrier
	s_setprio 1
	s_waitcnt lgkmcnt(0)
	s_cmpk_eq_u32 s37, 0x20
	s_cbranch_scc1 .Lmy_gska
; #define PG8_STAGE(bufoff, gbase, voff) do { _Pragma("unroll") for (int _i = 0; _i < 2; ++_i) \
;         __builtin_amdgcn_global_load_lds((const unsigned*)((const char*)(gbase) + (voff)[_i]), (PG8_LAS unsigned*)(lds + (bufoff) + ldsw + _i * 8192), 16, 0, 0); } while (0)
; #define PG8_LDA(dst, b, h) do { _Pragma("unroll") for (int m = 0; m < 4; ++m) _Pragma("unroll") for (int k = 0; k < 2; ++k) dst[m][k] = *(const PG8_LAS bf16x8*)(lds + PG8_SA(b, h) + aoff + m * 2048 + k * 1024); } while (0)
; #define PG8_LDB(dst, b, h) do { _Pragma("unroll") for (int n = 0; n < 2; ++n) _Pragma("unroll") for (int k = 0; k < 2; ++k) dst[n][k] = *(const PG8_LAS bf16x8*)(lds + PG8_SB(b, h) + boff + n * 2048 + k * 1024); } while (0)
; #define PG8_MMA(ai, bj, At, Bt) do { __builtin_amdgcn_s_setprio(1); _Pragma("unroll") for (int m = 0; m < 4; ++m) _Pragma("unroll") for (int n = 0; n < 2; ++n) _Pragma("unroll") for (int k = 0; k < 2; ++k) \
;         acc[ai][bj][m][n] = __builtin_amdgcn_mfma_f32_16x16x32_bf16(Bt[n][k], At[m][k], acc[ai][bj][m][n], 0, 0, 0); __builtin_amdgcn_s_setprio(0); } while (0)
; #define PG8_WAIT_V(n) asm volatile("s_waitcnt vmcnt(" #n ")" ::: "memory")
; #define PG8_WAIT_L(n) asm volatile("s_waitcnt lgkmcnt(" #n ")" ::: "memory")
; #define PG8_BAR __builtin_amdgcn_s_barrier()
; #define PG8_SCHED __builtin_amdgcn_sched_barrier(0)
; template <class Epi, class Sched, bool ALIGN_EPI = false, bool SP2 = false>
; __device__ __forceinline__ void gemm_phase(PG8_LAS unsigned char* lds, const Gemm g, const Sched& S, const Epi& E) {
;     ...
;             PG8_WAIT_V(8); PG8_WAIT_L(0); PG8_BAR; PG8_MMA(1, 0, At, B0); PG8_MMA(1, 1, At, B1); PG8_BAR; PG8_SCHED;
;             PG8_LDB(B0, 1, 0); PG8_LDB(B1, 1, 1); PG8_SCHED; PG8_LDA(At, 1, 0); PG8_STAGE(PG8_SA(0, 1), a2 + hstep, voffA);
;             PG8_WAIT_V(8); PG8_WAIT_L(0); PG8_BAR; PG8_MMA(0, 0, At, B0); PG8_MMA(0, 1, At, B1); PG8_BAR; PG8_SCHED;
	v_mfma_f32_16x16x32_bf16 v[92:95], v[120:123], v[170:173], v[92:95]
	v_mfma_f32_16x16x32_bf16 v[92:95], v[124:127], v[188:191], v[92:95]
	v_mfma_f32_16x16x32_bf16 v[84:87], v[120:123], v[192:195], v[84:87]
	v_mfma_f32_16x16x32_bf16 v[84:87], v[124:127], v[196:199], v[84:87]
	v_mfma_f32_16x16x32_bf16 v[76:79], v[120:123], v[200:203], v[76:79]
	v_mfma_f32_16x16x32_bf16 v[76:79], v[124:127], v[204:207], v[76:79]
	v_mfma_f32_16x16x32_bf16 v[108:111], v[120:123], v[242:245], v[108:111]
	v_mfma_f32_16x16x32_bf16 v[108:111], v[124:127], v[246:249], v[108:111]
	v_mfma_f32_16x16x32_bf16 v[44:47], v[128:131], v[242:245], v[44:47]
	v_mfma_f32_16x16x32_bf16 v[44:47], v[132:135], v[246:249], v[44:47]
	v_mfma_f32_16x16x32_bf16 v[12:15], v[128:131], v[200:203], v[12:15]
	v_mfma_f32_16x16x32_bf16 v[12:15], v[132:135], v[204:207], v[12:15]
	v_mfma_f32_16x16x32_bf16 v[20:23], v[128:131], v[192:195], v[20:23]
	v_mfma_f32_16x16x32_bf16 v[20:23], v[132:135], v[196:199], v[20:23]
	v_mfma_f32_16x16x32_bf16 v[28:31], v[128:131], v[170:173], v[28:31]
	v_mfma_f32_16x16x32_bf16 v[28:31], v[132:135], v[188:191], v[28:31]
	s_setprio 0
	s_setprio 1
	v_mfma_f32_16x16x32_bf16 v[88:91], v[136:139], v[170:173], v[88:91]
	v_mfma_f32_16x16x32_bf16 v[88:91], v[140:143], v[188:191], v[88:91]
	v_mfma_f32_16x16x32_bf16 v[80:83], v[136:139], v[192:195], v[80:83]
	v_mfma_f32_16x16x32_bf16 v[80:83], v[140:143], v[196:199], v[80:83]
	v_mfma_f32_16x16x32_bf16 v[72:75], v[136:139], v[200:203], v[72:75]
	v_mfma_f32_16x16x32_bf16 v[72:75], v[140:143], v[204:207], v[72:75]
	v_mfma_f32_16x16x32_bf16 v[104:107], v[136:139], v[242:245], v[104:107]
	v_mfma_f32_16x16x32_bf16 v[104:107], v[140:143], v[246:249], v[104:107]
	v_mfma_f32_16x16x32_bf16 v[40:43], v[162:165], v[242:245], v[40:43]
	v_mfma_f32_16x16x32_bf16 v[40:43], v[166:169], v[246:249], v[40:43]
	v_mfma_f32_16x16x32_bf16 v[8:11], v[162:165], v[200:203], v[8:11]
	v_mfma_f32_16x16x32_bf16 v[8:11], v[166:169], v[204:207], v[8:11]
	v_mfma_f32_16x16x32_bf16 v[16:19], v[162:165], v[192:195], v[16:19]
	v_mfma_f32_16x16x32_bf16 v[16:19], v[166:169], v[196:199], v[16:19]
	v_mfma_f32_16x16x32_bf16 v[24:27], v[162:165], v[170:173], v[24:27]
	v_mfma_f32_16x16x32_bf16 v[24:27], v[166:169], v[188:191], v[24:27]
.Lmy_gska:
	s_setprio 0
	s_barrier
	v_add_u32_e32 v0, s91, v230
	s_add_i32 s38, 0, 0x1c000
	ds_read_b128 v[120:123], v0
	ds_read_b128 v[124:127], v0 offset:1024
	ds_read_b128 v[128:131], v0 offset:2048
	ds_read_b128 v[132:135], v0 offset:3072
	v_add_u32_e32 v0, s38, v230
	ds_read_b128 v[136:139], v0
	ds_read_b128 v[140:143], v0 offset:1024
	ds_read_b128 v[162:165], v0 offset:2048
	ds_read_b128 v[166:169], v0 offset:3072
	s_add_u32 s86, s86, s48
	s_addc_u32 s87, s87, s49
	s_mov_b32 m0, s95
	v_lshl_add_u64 v[148:149], s[86:87], 0, v[2:3]
	ds_read_b128 v[170:173], v238 offset:32768
	ds_read_b128 v[188:191], v238 offset:33792
	ds_read_b128 v[192:195], v238 offset:34816
	ds_read_b128 v[196:199], v238 offset:35840
	ds_read_b128 v[200:203], v238 offset:36864
	ds_read_b128 v[204:207], v238 offset:37888
	ds_read_b128 v[242:245], v238 offset:38912
	ds_read_b128 v[246:249], v238 offset:39936
	global_load_lds_dwordx4 v[148:149], off
	v_lshl_add_u64 v[148:149], s[86:87], 0, v[178:179]
	s_mov_b32 m0, s96
	s_nop 0
	global_load_lds_dwordx4 v[148:149], off
	s_waitcnt vmcnt(8)
	s_waitcnt lgkmcnt(0)
	s_barrier
	s_setprio 1
	s_waitcnt lgkmcnt(0)
	v_mfma_f32_16x16x32_bf16 v[158:161], v[120:123], v[170:173], v[158:161]
	v_mfma_f32_16x16x32_bf16 v[158:161], v[124:127], v[188:191], v[158:161]
	v_mfma_f32_16x16x32_bf16 v[148:151], v[120:123], v[192:195], v[150:153]
	v_mfma_f32_16x16x32_bf16 v[150:153], v[124:127], v[196:199], v[148:151]
	v_mfma_f32_16x16x32_bf16 v[100:103], v[120:123], v[200:203], v[100:103]
	v_mfma_f32_16x16x32_bf16 v[100:103], v[124:127], v[204:207], v[100:103]
	v_mfma_f32_16x16x32_bf16 v[116:119], v[120:123], v[242:245], v[116:119]
	v_mfma_f32_16x16x32_bf16 v[116:119], v[124:127], v[246:249], v[116:119]
	v_mfma_f32_16x16x32_bf16 v[68:71], v[128:131], v[242:245], v[68:71]
	v_mfma_f32_16x16x32_bf16 v[68:71], v[132:135], v[246:249], v[68:71]
	v_mfma_f32_16x16x32_bf16 v[36:39], v[128:131], v[200:203], v[36:39]
	v_mfma_f32_16x16x32_bf16 v[36:39], v[132:135], v[204:207], v[36:39]
	v_mfma_f32_16x16x32_bf16 v[52:55], v[128:131], v[192:195], v[52:55]
	v_mfma_f32_16x16x32_bf16 v[52:55], v[132:135], v[196:199], v[52:55]
	v_mfma_f32_16x16x32_bf16 v[60:63], v[128:131], v[170:173], v[60:63]
	v_mfma_f32_16x16x32_bf16 v[60:63], v[132:135], v[188:191], v[60:63]
	s_setprio 0
	s_setprio 1
	v_mfma_f32_16x16x32_bf16 v[154:157], v[136:139], v[170:173], v[154:157]
	v_mfma_f32_16x16x32_bf16 v[154:157], v[140:143], v[188:191], v[154:157]
	v_mfma_f32_16x16x32_bf16 v[144:147], v[136:139], v[192:195], v[144:147]
	v_mfma_f32_16x16x32_bf16 v[146:149], v[140:143], v[196:199], v[144:147]
	v_mfma_f32_16x16x32_bf16 v[96:99], v[136:139], v[200:203], v[96:99]
	v_mfma_f32_16x16x32_bf16 v[96:99], v[140:143], v[204:207], v[96:99]
	v_mfma_f32_16x16x32_bf16 v[112:115], v[136:139], v[242:245], v[112:115]
	v_mfma_f32_16x16x32_bf16 v[112:115], v[140:143], v[246:249], v[112:115]
	v_mfma_f32_16x16x32_bf16 v[64:67], v[162:165], v[242:245], v[64:67]
	v_mfma_f32_16x16x32_bf16 v[64:67], v[166:169], v[246:249], v[64:67]
	v_mfma_f32_16x16x32_bf16 v[32:35], v[162:165], v[200:203], v[32:35]
	v_mfma_f32_16x16x32_bf16 v[32:35], v[166:169], v[204:207], v[32:35]
	v_mfma_f32_16x16x32_bf16 v[48:51], v[162:165], v[192:195], v[48:51]
	v_mfma_f32_16x16x32_bf16 v[48:51], v[166:169], v[196:199], v[48:51]
	v_mfma_f32_16x16x32_bf16 v[56:59], v[162:165], v[170:173], v[56:59]
	v_mfma_f32_16x16x32_bf16 v[56:59], v[166:169], v[188:191], v[56:59]
	s_setprio 0
	s_barrier
; #define PG8_STAGE(bufoff, gbase, voff) do { _Pragma("unroll") for (int _i = 0; _i < 2; ++_i) \
;         __builtin_amdgcn_global_load_lds((const unsigned*)((const char*)(gbase) + (voff)[_i]), (PG8_LAS unsigned*)(lds + (bufoff) + ldsw + _i * 8192), 16, 0, 0); } while (0)
; #define PG8_LDA(dst, b, h) do { _Pragma("unroll") for (int m = 0; m < 4; ++m) _Pragma("unroll") for (int k = 0; k < 2; ++k) dst[m][k] = *(const PG8_LAS bf16x8*)(lds + PG8_SA(b, h) + aoff + m * 2048 + k * 1024); } while (0)
; #define PG8_MMA(ai, bj, At, Bt) do { __builtin_amdgcn_s_setprio(1); _Pragma("unroll") for (int m = 0; m < 4; ++m) _Pragma("unroll") for (int n = 0; n < 2; ++n) _Pragma("unroll") for (int k = 0; k < 2; ++k) \
;         acc[ai][bj][m][n] = __builtin_amdgcn_mfma_f32_16x16x32_bf16(Bt[n][k], At[m][k], acc[ai][bj][m][n], 0, 0, 0); __builtin_amdgcn_s_setprio(0); } while (0)
; #define PG8_WAIT_V(n) asm volatile("s_waitcnt vmcnt(" #n ")" ::: "memory")
; #define PG8_WAIT_L(n) asm volatile("s_waitcnt lgkmcnt(" #n ")" ::: "memory")
; #define PG8_BAR __builtin_amdgcn_s_barrier()
; #define PG8_SCHED __builtin_amdgcn_sched_barrier(0)
; template <class Epi, class Sched, bool ALIGN_EPI = false, bool SP2 = false>
; __device__ __forceinline__ void gemm_phase(PG8_LAS unsigned char* lds, const Gemm g, const Sched& S, const Epi& E) {
;     ...
;             PG8_LDA(At, 1, 1); PG8_STAGE(PG8_SB(1, 0), b3, voffB); PG8_STAGE(PG8_SB(1, 1), b3 + hstep, voffB); PG8_STAGE(PG8_SA(1, 0), a3, voffA);
;             PG8_WAIT_V(8); PG8_WAIT_L(0); PG8_BAR; PG8_MMA(1, 0, At, B0); PG8_MMA(1, 1, At, B1); PG8_BAR; PG8_SCHED;
	s_add_i32 s39, s91, s92
	v_lshl_add_u64 v[144:145], v[174:175], 0, s[24:25]
	s_mov_b32 m0, s39
	ds_read_b128 v[170:173], v238 offset:49152
	ds_read_b128 v[188:191], v238 offset:50176
	ds_read_b128 v[192:195], v238 offset:51200
	ds_read_b128 v[196:199], v238 offset:52224
	ds_read_b128 v[200:203], v238 offset:53248
	ds_read_b128 v[204:207], v238 offset:54272
	ds_read_b128 v[242:245], v238 offset:55296
	ds_read_b128 v[246:249], v238 offset:56320
	global_load_lds_dwordx4 v[144:145], off
	v_lshl_add_u64 v[144:145], v[208:209], 0, s[24:25]
	s_add_i32 m0, s39, 0x2000
	s_add_i32 s38, s38, s92
	global_load_lds_dwordx4 v[144:145], off
	v_lshl_add_u64 v[144:145], v[216:217], 0, s[24:25]
	s_mov_b32 m0, s38
	s_nop 0
	global_load_lds_dwordx4 v[144:145], off
	v_lshl_add_u64 v[144:145], v[224:225], 0, s[24:25]
	s_add_i32 m0, s38, 0x2000
	s_nop 0
	global_load_lds_dwordx4 v[144:145], off
	v_lshl_add_u64 v[144:145], v[226:227], 0, s[24:25]
	s_mov_b32 m0, s10
	s_nop 0
	global_load_lds_dwordx4 v[144:145], off
	v_lshl_add_u64 v[144:145], v[228:229], 0, s[24:25]
	s_mov_b32 m0, s11
	s_nop 0
	global_load_lds_dwordx4 v[144:145], off
	s_waitcnt vmcnt(8)
	s_waitcnt lgkmcnt(0)
	s_barrier
	s_setprio 1
	s_waitcnt lgkmcnt(0)
	s_cmpk_eq_u32 s37, 0x20
	s_cbranch_scc1 .Lmy_gskb
	v_mfma_f32_16x16x32_bf16 v[92:95], v[120:123], v[170:173], v[92:95]
	v_mfma_f32_16x16x32_bf16 v[92:95], v[124:127], v[188:191], v[92:95]
	v_mfma_f32_16x16x32_bf16 v[84:87], v[120:123], v[192:195], v[84:87]
	v_mfma_f32_16x16x32_bf16 v[84:87], v[124:127], v[196:199], v[84:87]
	v_mfma_f32_16x16x32_bf16 v[76:79], v[120:123], v[200:203], v[76:79]
	v_mfma_f32_16x16x32_bf16 v[76:79], v[124:127], v[204:207], v[76:79]
	v_mfma_f32_16x16x32_bf16 v[108:111], v[120:123], v[242:245], v[108:111]
	v_mfma_f32_16x16x32_bf16 v[108:111], v[124:127], v[246:249], v[108:111]
	v_mfma_f32_16x16x32_bf16 v[44:47], v[128:131], v[242:245], v[44:47]
	v_mfma_f32_16x16x32_bf16 v[44:47], v[132:135], v[246:249], v[44:47]
	v_mfma_f32_16x16x32_bf16 v[12:15], v[128:131], v[200:203], v[12:15]
	v_mfma_f32_16x16x32_bf16 v[12:15], v[132:135], v[204:207], v[12:15]
	v_mfma_f32_16x16x32_bf16 v[20:23], v[128:131], v[192:195], v[20:23]
	v_mfma_f32_16x16x32_bf16 v[20:23], v[132:135], v[196:199], v[20:23]
	v_mfma_f32_16x16x32_bf16 v[28:31], v[128:131], v[170:173], v[28:31]
	v_mfma_f32_16x16x32_bf16 v[28:31], v[132:135], v[188:191], v[28:31]
	s_setprio 0
	s_setprio 1
	v_mfma_f32_16x16x32_bf16 v[88:91], v[136:139], v[170:173], v[88:91]
	v_mfma_f32_16x16x32_bf16 v[88:91], v[140:143], v[188:191], v[88:91]
	v_mfma_f32_16x16x32_bf16 v[80:83], v[136:139], v[192:195], v[80:83]
	v_mfma_f32_16x16x32_bf16 v[80:83], v[140:143], v[196:199], v[80:83]
	v_mfma_f32_16x16x32_bf16 v[72:75], v[136:139], v[200:203], v[72:75]
	v_mfma_f32_16x16x32_bf16 v[72:75], v[140:143], v[204:207], v[72:75]
	v_mfma_f32_16x16x32_bf16 v[104:107], v[136:139], v[242:245], v[104:107]
	v_mfma_f32_16x16x32_bf16 v[104:107], v[140:143], v[246:249], v[104:107]
	v_mfma_f32_16x16x32_bf16 v[40:43], v[162:165], v[242:245], v[40:43]
	v_mfma_f32_16x16x32_bf16 v[40:43], v[166:169], v[246:249], v[40:43]
	v_mfma_f32_16x16x32_bf16 v[8:11], v[162:165], v[200:203], v[8:11]
	v_mfma_f32_16x16x32_bf16 v[8:11], v[166:169], v[204:207], v[8:11]
	v_mfma_f32_16x16x32_bf16 v[16:19], v[162:165], v[192:195], v[16:19]
	v_mfma_f32_16x16x32_bf16 v[16:19], v[166:169], v[196:199], v[16:19]
	v_mfma_f32_16x16x32_bf16 v[24:27], v[162:165], v[170:173], v[24:27]
	v_mfma_f32_16x16x32_bf16 v[24:27], v[166:169], v[188:191], v[24:27]
.Lmy_gskb:
	s_setprio 0
	s_barrier
	s_add_u32 s0, s0, 0x100
	s_addc_u32 s1, s1, 0
	s_add_u32 s72, s72, 0x100
	s_addc_u32 s73, s73, 0
	s_cmp_ge_u32 s88, s9
	s_mov_b32 s86, s88
	s_cbranch_scc0 .LBB0_365
